# speedup vs baseline: 1.0982x; 1.0057x over previous
; __device__ __forceinline__ void phase_fox_attn(const Params& p, char* smem) {
;     ...
;       f32x4 s[4][2];
; #pragma unroll
;       for (int kb = 0; kb < 4; ++kb) { s[kb][0] = (f32x4){0.f, 0.f, 0.f, 0.f}; s[kb][1] = (f32x4){0.f, 0.f, 0.f, 0.f}; }
;       int kb_ = kbase, vb_ = vbase;
;       asm volatile("" : "+v"(kb_), "+v"(vb_));
;       __builtin_amdgcn_s_setprio(1);
; #pragma unroll
;       for (int ks = 0; ks < 4; ++ks) {
;         const int ko = kb_ ^ (ks << 6);
; #pragma unroll
;         for (int kb = 0; kb < 4; ++kb) {
;           bf16x8 a = *(const bf16x8*)(sK + kb * 4096 + ko);
;           s[kb][0] = __builtin_amdgcn_mfma_f32_16x16x32_bf16(a, qf[0][ks], s[kb][0], 0, 0, 0);
;           s[kb][1] = __builtin_amdgcn_mfma_f32_16x16x32_bf16(a, qf[1][ks], s[kb][1], 0, 0, 0);
;         }
;       }
;       __builtin_amdgcn_s_setprio(0);
;       const bool diag = (t >= nkv - 2);
;       float mx2[2];
; #pragma unroll
;       for (int qb = 0; qb < 2; ++qb) {
;         const int qpos = q0 + wave * 32 + qb * 16 + lr;
;         float mx = -INFINITY;
; #pragma unroll
;         for (int kb = 0; kb < 4; ++kb)
; #pragma unroll
;           for (int r = 0; r < 4; ++r) {
;             int kl = kb * 16 + g * 4 + r;
;             float v = s[kb][qb][r] + (ct[qb] - sCt[kl]);
;             if (diag && (kv0 + kl > qpos)) v = -INFINITY;
;             s[kb][qb][r] = v;
;             mx = fmaxf(mx, v);
;           }
.LBB0_203:
	s_lshl_b32 s4, s87, 14
	s_add_i32 s6, s4, 0
	v_mov_b32_e32 v139, v132
	v_mov_b32_e32 v104, v133
	s_setprio 1
	v_add_u32_e32 v143, s6, v139
	ds_read_b128 v[96:99], v143
	ds_read_b128 v[100:103], v143 offset:4096
	ds_read_b128 v[150:153], v143 offset:8192
	ds_read_b128 v[158:161], v143 offset:12288
	v_xad_u32 v143, v139, 64, s6
	ds_read_b128 v[170:173], v143
	ds_read_b128 v[174:177], v143 offset:4096
	s_waitcnt lgkmcnt(0)
	v_mfma_f32_16x16x32_bf16 v[126:129], v[96:99], v[92:95], 0
	v_mfma_f32_16x16x32_bf16 v[96:99], v[96:99], v[76:79], 0
	v_mfma_f32_16x16x32_bf16 v[146:149], v[100:103], v[92:95], 0
	v_mfma_f32_16x16x32_bf16 v[100:103], v[100:103], v[76:79], 0
	v_mfma_f32_16x16x32_bf16 v[126:129], v[170:173], v[64:67], v[126:129]
	v_mfma_f32_16x16x32_bf16 v[96:99], v[170:173], v[80:83], v[96:99]
	v_mfma_f32_16x16x32_bf16 v[146:149], v[174:177], v[64:67], v[146:149]
	v_mfma_f32_16x16x32_bf16 v[100:103], v[174:177], v[80:83], v[100:103]
	ds_read_b128 v[170:173], v143 offset:8192
	ds_read_b128 v[174:177], v143 offset:12288
	v_xor_b32_e32 v143, 0x80, v139
	v_add_u32_e32 v143, s6, v143
	v_mfma_f32_16x16x32_bf16 v[162:165], v[150:153], v[92:95], 0
	v_xor_b32_e32 v139, 0xc0, v139
	v_add_u32_e32 v139, s6, v139
	v_mfma_f32_16x16x32_bf16 v[150:153], v[150:153], v[76:79], 0
	v_mfma_f32_16x16x32_bf16 v[166:169], v[158:161], v[92:95], 0
	v_mfma_f32_16x16x32_bf16 v[158:161], v[158:161], v[76:79], 0
	s_waitcnt lgkmcnt(0)
	v_mfma_f32_16x16x32_bf16 v[162:165], v[170:173], v[64:67], v[162:165]
	v_mfma_f32_16x16x32_bf16 v[150:153], v[170:173], v[80:83], v[150:153]
	v_mfma_f32_16x16x32_bf16 v[166:169], v[174:177], v[64:67], v[166:169]
	v_mfma_f32_16x16x32_bf16 v[158:161], v[174:177], v[80:83], v[158:161]
	ds_read_b128 v[170:173], v143
	ds_read_b128 v[174:177], v143 offset:4096
	s_waitcnt lgkmcnt(0)
	v_mfma_f32_16x16x32_bf16 v[126:129], v[170:173], v[68:71], v[126:129]
	v_mfma_f32_16x16x32_bf16 v[96:99], v[170:173], v[84:87], v[96:99]
	v_mfma_f32_16x16x32_bf16 v[146:149], v[174:177], v[68:71], v[146:149]
	v_mfma_f32_16x16x32_bf16 v[100:103], v[174:177], v[84:87], v[100:103]
	ds_read_b128 v[170:173], v143 offset:8192
	ds_read_b128 v[174:177], v143 offset:12288
	s_waitcnt lgkmcnt(0)
	v_mfma_f32_16x16x32_bf16 v[162:165], v[170:173], v[68:71], v[162:165]
	v_mfma_f32_16x16x32_bf16 v[150:153], v[170:173], v[84:87], v[150:153]
	v_mfma_f32_16x16x32_bf16 v[166:169], v[174:177], v[68:71], v[166:169]
	v_mfma_f32_16x16x32_bf16 v[158:161], v[174:177], v[84:87], v[158:161]
	ds_read_b128 v[170:173], v139
	ds_read_b128 v[174:177], v139 offset:4096
	s_waitcnt lgkmcnt(0)
	v_mfma_f32_16x16x32_bf16 v[178:181], v[170:173], v[72:75], v[126:129]
	v_mfma_f32_16x16x32_bf16 v[170:173], v[170:173], v[88:91], v[96:99]
	s_nop 2
	ds_read_b128 v[96:99], v139 offset:8192
	ds_read_b128 v[126:129], v139 offset:12288
	v_mfma_f32_16x16x32_bf16 v[182:185], v[174:177], v[72:75], v[146:149]
	v_mfma_f32_16x16x32_bf16 v[174:177], v[174:177], v[88:91], v[100:103]
	s_waitcnt lgkmcnt(0)
	v_mfma_f32_16x16x32_bf16 v[162:165], v[96:99], v[72:75], v[162:165]
	v_mfma_f32_16x16x32_bf16 v[100:103], v[96:99], v[88:91], v[150:153]
	v_mfma_f32_16x16x32_bf16 v[166:169], v[126:129], v[72:75], v[166:169]
	v_mfma_f32_16x16x32_bf16 v[96:99], v[126:129], v[88:91], v[158:161]
	s_setprio 0
	v_mbcnt_hi_u32_b32 v126, -1, v156
	v_and_b32_e32 v128, 64, v126
	v_lshl_add_u32 v151, s87, 8, v136
	v_xor_b32_e32 v127, 16, v126
	v_add_u32_e32 v128, 64, v128
	ds_read_b128 v[186:189], v151
	ds_read_b128 v[190:193], v151 offset:64
	v_cmp_lt_i32_e32 vcc, v127, v128
	v_add_u32_e32 v159, s86, v123
	s_cmp_ge_i32 s84, s3
	v_cndmask_b32_e32 v129, v126, v127, vcc
	v_lshlrev_b32_e32 v194, 2, v129
	v_xor_b32_e32 v129, 32, v126
	v_cmp_lt_i32_e32 vcc, v129, v128
	v_add_u32_e32 v160, 0xfc0, v159
	s_cselect_b64 s[4:5], -1, 0
	s_cbranch_scc0 .Lfox_fast
	v_cndmask_b32_e32 v195, v126, v129, vcc
	s_waitcnt lgkmcnt(0)
	v_sub_f32_e32 v139, v130, v186
	v_cmp_gt_i32_e32 vcc, v160, v134
	v_add_f32_e32 v139, v178, v139
	s_and_b64 vcc, s[4:5], vcc
	v_add_u32_e32 v161, 0xfc1, v159
	v_cndmask_b32_e32 v139, v139, v122, vcc
	v_sub_f32_e32 v143, v130, v187
	v_cmp_gt_i32_e32 vcc, v161, v134
	v_add_f32_e32 v143, v179, v143
	s_and_b64 vcc, s[4:5], vcc
	v_add_u32_e32 v196, 0xfc2, v159
	v_cndmask_b32_e32 v143, v143, v122, vcc
	v_sub_f32_e32 v145, v130, v188
	v_cmp_gt_i32_e32 vcc, v196, v134
	v_add_f32_e32 v145, v180, v145
	s_and_b64 vcc, s[4:5], vcc
	v_add_u32_e32 v197, 0xfc3, v159
	v_cndmask_b32_e32 v145, v145, v122, vcc
	v_sub_f32_e32 v146, v130, v189
	v_cmp_gt_i32_e32 vcc, v197, v134
	v_add_f32_e32 v146, v181, v146
	s_and_b64 vcc, s[4:5], vcc
	v_max3_f32 v147, v139, s0, v143
	v_cndmask_b32_e32 v146, v146, v122, vcc
	v_add_u32_e32 v198, 0xfd0, v159
	v_max3_f32 v149, v147, v145, v146
	v_sub_f32_e32 v147, v130, v190
	v_cmp_gt_i32_e32 vcc, v198, v134
	v_add_f32_e32 v147, v182, v147
	s_and_b64 vcc, s[4:5], vcc
	v_add_u32_e32 v199, 0xfd1, v159
	v_cndmask_b32_e32 v147, v147, v122, vcc
	v_sub_f32_e32 v148, v130, v191
	v_cmp_gt_i32_e32 vcc, v199, v134
	v_add_f32_e32 v148, v183, v148
	s_and_b64 vcc, s[4:5], vcc
	v_cndmask_b32_e32 v148, v148, v122, vcc
	v_add_u32_e32 v200, 0xfd2, v159
	ds_read_b128 v[178:181], v151 offset:128
	v_max3_f32 v152, v149, v147, v148
	v_sub_f32_e32 v149, v130, v192
	v_cmp_gt_i32_e32 vcc, v200, v134
	v_add_f32_e32 v149, v184, v149
	s_and_b64 vcc, s[4:5], vcc
	v_add_u32_e32 v201, 0xfd3, v159
	v_cndmask_b32_e32 v149, v149, v122, vcc
	v_sub_f32_e32 v150, v130, v193
	v_cmp_gt_i32_e32 vcc, v201, v134
	v_add_f32_e32 v150, v185, v150
	s_and_b64 vcc, s[4:5], vcc
	v_add_u32_e32 v202, 0xfe0, v159
	v_cndmask_b32_e32 v150, v150, v122, vcc
	ds_read_b128 v[182:185], v151 offset:192
	s_waitcnt lgkmcnt(0)
; __device__ __forceinline__ void phase_fox_attn(const Params& p, char* smem) {
;     ...
; #pragma unroll
;       for (int qb = 0; qb < 2; ++qb) {
;         const int qpos = q0 + wave * 32 + qb * 16 + lr;
;         float mx = -INFINITY;
; #pragma unroll
;         for (int kb = 0; kb < 4; ++kb)
; #pragma unroll
;           for (int r = 0; r < 4; ++r) {
;             int kl = kb * 16 + g * 4 + r;
;             float v = s[kb][qb][r] + (ct[qb] - sCt[kl]);
;             if (diag && (kv0 + kl > qpos)) v = -INFINITY;
;             s[kb][qb][r] = v;
;             mx = fmaxf(mx, v);
;           }
	v_sub_f32_e32 v151, v130, v178
	v_cmp_gt_i32_e32 vcc, v202, v134
	v_add_f32_e32 v151, v162, v151
	s_and_b64 vcc, s[4:5], vcc
	v_add_u32_e32 v203, 0xfe1, v159
	v_max3_f32 v153, v152, v149, v150
	v_cndmask_b32_e32 v151, v151, v122, vcc
	v_sub_f32_e32 v152, v130, v179
	v_cmp_gt_i32_e32 vcc, v203, v134
	v_add_f32_e32 v152, v163, v152
	s_and_b64 vcc, s[4:5], vcc
	v_cndmask_b32_e32 v152, v152, v122, vcc
	v_add_u32_e32 v204, 0xfe2, v159
	v_max3_f32 v155, v153, v151, v152
	v_sub_f32_e32 v153, v130, v180
	v_cmp_gt_i32_e32 vcc, v204, v134
	v_add_f32_e32 v153, v164, v153
	s_and_b64 vcc, s[4:5], vcc
	v_add_u32_e32 v205, 0xfe3, v159
	v_cndmask_b32_e32 v153, v153, v122, vcc
	v_sub_f32_e32 v154, v130, v181
	v_cmp_gt_i32_e32 vcc, v205, v134
	v_add_f32_e32 v154, v165, v154
	s_and_b64 vcc, s[4:5], vcc
	v_cndmask_b32_e32 v154, v154, v122, vcc
	v_add_u32_e32 v206, 0xff0, v159
	v_max3_f32 v158, v155, v153, v154
	v_sub_f32_e32 v155, v130, v182
	v_cmp_gt_i32_e32 vcc, v206, v134
	v_add_f32_e32 v155, v166, v155
	s_and_b64 vcc, s[4:5], vcc
	v_add_u32_e32 v207, 0xff1, v159
	v_cndmask_b32_e32 v155, v155, v122, vcc
	v_sub_f32_e32 v157, v130, v183
	v_cmp_gt_i32_e32 vcc, v207, v134
	v_add_f32_e32 v157, v167, v157
	s_and_b64 vcc, s[4:5], vcc
	v_cndmask_b32_e32 v157, v157, v122, vcc
	v_max3_f32 v162, v158, v155, v157
	v_sub_f32_e32 v158, v130, v184
	v_add_f32_e32 v158, v168, v158
	v_add_u32_e32 v168, 0xff2, v159
	v_cmp_gt_i32_e32 vcc, v168, v134
	v_sub_f32_e32 v163, v130, v185
	s_and_b64 vcc, s[4:5], vcc
	v_add_f32_e32 v163, v169, v163
	v_add_u32_e32 v169, 0xff3, v159
	v_cndmask_b32_e32 v158, v158, v122, vcc
	v_cmp_gt_i32_e32 vcc, v169, v134
	s_and_b64 vcc, s[4:5], vcc
	s_nop 0
	v_cndmask_b32_e32 v159, v163, v122, vcc
	v_max3_f32 v208, v162, v158, v159
	v_sub_f32_e32 v162, v131, v186
	v_cmp_gt_i32_e32 vcc, v160, v135
	v_add_f32_e32 v162, v170, v162
	s_and_b64 vcc, s[4:5], vcc
	v_cndmask_b32_e32 v160, v162, v122, vcc
	v_sub_f32_e32 v162, v131, v187
	v_cmp_gt_i32_e32 vcc, v161, v135
	v_add_f32_e32 v162, v171, v162
	s_and_b64 vcc, s[4:5], vcc
	v_cndmask_b32_e32 v161, v162, v122, vcc
	v_sub_f32_e32 v163, v131, v188
	v_cmp_gt_i32_e32 vcc, v196, v135
	v_add_f32_e32 v163, v172, v163
	s_and_b64 vcc, s[4:5], vcc
	v_cndmask_b32_e32 v164, v163, v122, vcc
	v_sub_f32_e32 v163, v131, v189
	v_cmp_gt_i32_e32 vcc, v197, v135
	v_add_f32_e32 v163, v173, v163
	s_and_b64 vcc, s[4:5], vcc
	v_cndmask_b32_e32 v165, v163, v122, vcc
	v_sub_f32_e32 v163, v131, v190
	v_cmp_gt_i32_e32 vcc, v198, v135
	v_add_f32_e32 v163, v174, v163
	s_and_b64 vcc, s[4:5], vcc
	v_cndmask_b32_e32 v166, v163, v122, vcc
	v_sub_f32_e32 v163, v131, v191
	v_cmp_gt_i32_e32 vcc, v199, v135
	v_max3_f32 v162, v160, s0, v161
	v_add_f32_e32 v163, v175, v163
	s_and_b64 vcc, s[4:5], vcc
	v_max3_f32 v162, v162, v164, v165
	v_cndmask_b32_e32 v167, v163, v122, vcc
	v_max3_f32 v170, v162, v166, v167
	v_sub_f32_e32 v162, v131, v192
	v_cmp_gt_i32_e32 vcc, v200, v135
	v_add_f32_e32 v162, v176, v162
	s_and_b64 vcc, s[4:5], vcc
	v_cndmask_b32_e32 v162, v162, v122, vcc
	v_sub_f32_e32 v163, v131, v193
	v_cmp_gt_i32_e32 vcc, v201, v135
	v_add_f32_e32 v163, v177, v163
	s_and_b64 vcc, s[4:5], vcc
	v_cndmask_b32_e32 v163, v163, v122, vcc
	v_sub_f32_e32 v171, v131, v178
	v_cmp_gt_i32_e32 vcc, v202, v135
	v_add_f32_e32 v100, v100, v171
	s_and_b64 vcc, s[4:5], vcc
	v_cndmask_b32_e32 v100, v100, v122, vcc
	v_sub_f32_e32 v171, v131, v179
	v_cmp_gt_i32_e32 vcc, v203, v135
	v_add_f32_e32 v101, v101, v171
	s_and_b64 vcc, s[4:5], vcc
	v_cndmask_b32_e32 v101, v101, v122, vcc
	v_sub_f32_e32 v171, v131, v180
	v_cmp_gt_i32_e32 vcc, v204, v135
	v_add_f32_e32 v102, v102, v171
	s_and_b64 vcc, s[4:5], vcc
	v_cndmask_b32_e32 v102, v102, v122, vcc
	v_sub_f32_e32 v171, v131, v181
	v_cmp_gt_i32_e32 vcc, v205, v135
	v_add_f32_e32 v103, v103, v171
	s_and_b64 vcc, s[4:5], vcc
	v_cndmask_b32_e32 v103, v103, v122, vcc
	v_sub_f32_e32 v171, v131, v182
	v_cmp_gt_i32_e32 vcc, v206, v135
	v_add_f32_e32 v96, v96, v171
	s_and_b64 vcc, s[4:5], vcc
	v_cndmask_b32_e32 v96, v96, v122, vcc
	v_sub_f32_e32 v171, v131, v183
	v_cmp_gt_i32_e32 vcc, v207, v135
	v_add_f32_e32 v97, v97, v171
	s_and_b64 vcc, s[4:5], vcc
	v_cndmask_b32_e32 v97, v97, v122, vcc
	v_sub_f32_e32 v171, v131, v184
	v_cmp_gt_i32_e32 vcc, v168, v135
	v_max3_f32 v170, v170, v162, v163
	v_add_f32_e32 v98, v98, v171
	s_and_b64 vcc, s[4:5], vcc
	v_max3_f32 v170, v170, v100, v101
	v_cndmask_b32_e32 v98, v98, v122, vcc
	v_sub_f32_e32 v168, v131, v185
	v_cmp_gt_i32_e32 vcc, v169, v135
	v_max3_f32 v170, v170, v102, v103
	v_add_f32_e32 v99, v99, v168
	s_and_b64 vcc, s[4:5], vcc
	v_max3_f32 v170, v170, v96, v97
	v_cndmask_b32_e32 v99, v99, v122, vcc
; __device__ __forceinline__ void phase_fox_attn(const Params& p, char* smem) {
;     ...
; #pragma unroll
;       for (int qb = 0; qb < 2; ++qb) {
;         const int qpos = q0 + wave * 32 + qb * 16 + lr;
;         float mx = -INFINITY;
; #pragma unroll
;         for (int kb = 0; kb < 4; ++kb)
; #pragma unroll
;           for (int r = 0; r < 4; ++r) {
;             int kl = kb * 16 + g * 4 + r;
;             float v = s[kb][qb][r] + (ct[qb] - sCt[kl]);
;             if (diag && (kv0 + kl > qpos)) v = -INFINITY;
;             s[kb][qb][r] = v;
;             mx = fmaxf(mx, v);
;           }
;         mx = fmaxf(mx, __shfl_xor(mx, 16));
;         mx = fmaxf(mx, __shfl_xor(mx, 32));
;         mx2[qb] = mx;
;       }
;       if (__any((mx2[0] > m[0] + 8.f) || (mx2[1] > m[1] + 8.f))) {
; #pragma unroll
;         for (int qb = 0; qb < 2; ++qb) {
;           const float mnew = fmaxf(m[qb], mx2[qb]);
;           const float alpha = (mnew == -INFINITY) ? 1.f : __builtin_amdgcn_exp2f(m[qb] - mnew);
;           m[qb] = mnew;
;           l[qb] *= alpha;
; #pragma unroll
;           for (int db = 0; db < 8; ++db) { o[db][qb][0] *= alpha; o[db][qb][1] *= alpha; o[db][qb][2] *= alpha; o[db][qb][3] *= alpha; }
;         }
.Lfox_join:
	v_max3_f32 v168, v170, v98, v99
	ds_bpermute_b32 v209, v194, v208
	ds_bpermute_b32 v169, v194, v168
	v_lshlrev_b32_e32 v170, 2, v195
	s_waitcnt lgkmcnt(0)
	v_max_f32_e32 v171, v209, v209
	v_max_f32_e32 v169, v169, v169
	v_max_f32_e32 v171, v208, v171
	v_max_f32_e32 v168, v168, v169
	ds_bpermute_b32 v172, v170, v171
	ds_bpermute_b32 v170, v170, v168
	s_waitcnt lgkmcnt(0)
	v_max_f32_e32 v169, v172, v172
	v_max_f32_e32 v170, v170, v170
	v_max_f32_e32 v169, v171, v169
	v_max_f32_e32 v168, v168, v170
	v_add_f32_e32 v170, 0x41000000, v138
	v_cmp_gt_f32_e32 vcc, v169, v170
	v_add_f32_e32 v170, 0x41000000, v137
	v_cmp_gt_f32_e64 s[4:5], v168, v170
	s_or_b64 vcc, vcc, s[4:5]
	s_cbranch_vccz .LBB0_200
	v_max_f32_e32 v169, v169, v169
	v_max_f32_e32 v170, v138, v138
	v_max_f32_e32 v170, v170, v169
	v_max_f32_e32 v168, v168, v168
	v_max_f32_e32 v169, v137, v137
	v_sub_f32_e32 v138, v138, v170
	v_max_f32_e32 v171, v169, v168
	v_exp_f32_e32 v138, v138
	v_sub_f32_e32 v137, v137, v171
	v_exp_f32_e32 v137, v137
	v_cmp_neq_f32_e32 vcc, s0, v170
	s_nop 1
	v_cndmask_b32_e32 v169, 1.0, v138, vcc
	v_cmp_neq_f32_e32 vcc, s0, v171
	v_mov_b32_e32 v138, v169
	v_pk_mul_f32 v[50:51], v[50:51], v[138:139] op_sel_hi:[1,0]
	v_cndmask_b32_e32 v168, 1.0, v137, vcc
	v_pk_mul_f32 v[48:49], v[48:49], v[138:139] op_sel_hi:[1,0]
	v_pk_mul_f32 v[54:55], v[54:55], v[138:139] op_sel_hi:[1,0]
	v_pk_mul_f32 v[52:53], v[52:53], v[138:139] op_sel_hi:[1,0]
	v_pk_mul_f32 v[58:59], v[58:59], v[138:139] op_sel_hi:[1,0]
	v_pk_mul_f32 v[56:57], v[56:57], v[138:139] op_sel_hi:[1,0]
	v_pk_mul_f32 v[62:63], v[62:63], v[138:139] op_sel_hi:[1,0]
	v_pk_mul_f32 v[60:61], v[60:61], v[138:139] op_sel_hi:[1,0]
	v_pk_mul_f32 v[46:47], v[46:47], v[138:139] op_sel_hi:[1,0]
	v_pk_mul_f32 v[44:45], v[44:45], v[138:139] op_sel_hi:[1,0]
	v_pk_mul_f32 v[42:43], v[42:43], v[138:139] op_sel_hi:[1,0]
	v_pk_mul_f32 v[40:41], v[40:41], v[138:139] op_sel_hi:[1,0]
	v_pk_mul_f32 v[38:39], v[38:39], v[138:139] op_sel_hi:[1,0]
	v_pk_mul_f32 v[36:37], v[36:37], v[138:139] op_sel_hi:[1,0]
	v_pk_mul_f32 v[34:35], v[34:35], v[138:139] op_sel_hi:[1,0]
	v_pk_mul_f32 v[32:33], v[32:33], v[138:139] op_sel_hi:[1,0]
	v_pk_mul_f32 v[108:109], v[108:109], v[168:169]
	v_pk_mul_f32 v[30:31], v[30:31], v[168:169] op_sel_hi:[1,0]
	v_pk_mul_f32 v[28:29], v[28:29], v[168:169] op_sel_hi:[1,0]
	v_pk_mul_f32 v[26:27], v[26:27], v[168:169] op_sel_hi:[1,0]
	v_pk_mul_f32 v[24:25], v[24:25], v[168:169] op_sel_hi:[1,0]
	v_pk_mul_f32 v[22:23], v[22:23], v[168:169] op_sel_hi:[1,0]
	v_pk_mul_f32 v[20:21], v[20:21], v[168:169] op_sel_hi:[1,0]
	v_pk_mul_f32 v[18:19], v[18:19], v[168:169] op_sel_hi:[1,0]
	v_pk_mul_f32 v[16:17], v[16:17], v[168:169] op_sel_hi:[1,0]
	v_pk_mul_f32 v[14:15], v[14:15], v[168:169] op_sel_hi:[1,0]
	v_pk_mul_f32 v[12:13], v[12:13], v[168:169] op_sel_hi:[1,0]
	v_pk_mul_f32 v[10:11], v[10:11], v[168:169] op_sel_hi:[1,0]
	v_pk_mul_f32 v[8:9], v[8:9], v[168:169] op_sel_hi:[1,0]
	v_pk_mul_f32 v[6:7], v[6:7], v[168:169] op_sel_hi:[1,0]
	v_pk_mul_f32 v[4:5], v[4:5], v[168:169] op_sel_hi:[1,0]
	v_pk_mul_f32 v[2:3], v[2:3], v[168:169] op_sel_hi:[1,0]
	v_pk_mul_f32 v[0:1], v[0:1], v[168:169] op_sel_hi:[1,0]
	v_mov_b32_e32 v137, v171
	v_mov_b32_e32 v138, v170
	s_branch .LBB0_200
.Lfox_fast:
	v_cndmask_b32_e32 v195, v126, v129, vcc
	s_waitcnt lgkmcnt(0)
	v_sub_f32_e32 v139, v130, v186
	v_add_f32_e32 v139, v178, v139
	v_sub_f32_e32 v143, v130, v187
	v_add_f32_e32 v143, v179, v143
	v_sub_f32_e32 v145, v130, v188
	v_add_f32_e32 v145, v180, v145
	v_sub_f32_e32 v146, v130, v189
	v_add_f32_e32 v146, v181, v146
	v_max3_f32 v147, v139, s0, v143
	v_max3_f32 v149, v147, v145, v146
	v_sub_f32_e32 v147, v130, v190
	v_add_f32_e32 v147, v182, v147
	v_sub_f32_e32 v148, v130, v191
	v_add_f32_e32 v148, v183, v148
	ds_read_b128 v[178:181], v151 offset:128
	v_max3_f32 v152, v149, v147, v148
	v_sub_f32_e32 v149, v130, v192
	v_add_f32_e32 v149, v184, v149
	v_sub_f32_e32 v150, v130, v193
	v_add_f32_e32 v150, v185, v150
	ds_read_b128 v[182:185], v151 offset:192
	s_waitcnt lgkmcnt(0)
	v_sub_f32_e32 v151, v130, v178
	v_add_f32_e32 v151, v162, v151
	v_max3_f32 v153, v152, v149, v150
	v_sub_f32_e32 v152, v130, v179
	v_add_f32_e32 v152, v163, v152
	v_max3_f32 v155, v153, v151, v152
	v_sub_f32_e32 v153, v130, v180
	v_add_f32_e32 v153, v164, v153
	v_sub_f32_e32 v154, v130, v181
	v_add_f32_e32 v154, v165, v154
	v_max3_f32 v158, v155, v153, v154
	v_sub_f32_e32 v155, v130, v182
	v_add_f32_e32 v155, v166, v155
	v_sub_f32_e32 v157, v130, v183
	v_add_f32_e32 v157, v167, v157
	v_max3_f32 v162, v158, v155, v157
	v_sub_f32_e32 v158, v130, v184
	v_add_f32_e32 v158, v168, v158
	v_sub_f32_e32 v163, v130, v185
	v_add_f32_e32 v163, v169, v163
	s_nop 0
	v_mov_b32_e32 v159, v163
	v_max3_f32 v208, v162, v158, v159
	v_sub_f32_e32 v162, v131, v186
	v_add_f32_e32 v162, v170, v162
	v_mov_b32_e32 v160, v162
	v_sub_f32_e32 v162, v131, v187
	v_add_f32_e32 v162, v171, v162
	v_mov_b32_e32 v161, v162
	v_sub_f32_e32 v163, v131, v188
	v_add_f32_e32 v163, v172, v163
	v_mov_b32_e32 v164, v163
	v_sub_f32_e32 v163, v131, v189
	v_add_f32_e32 v163, v173, v163
	v_mov_b32_e32 v165, v163
	v_sub_f32_e32 v163, v131, v190
	v_add_f32_e32 v163, v174, v163
	v_mov_b32_e32 v166, v163
	v_sub_f32_e32 v163, v131, v191
	v_max3_f32 v162, v160, s0, v161
	v_add_f32_e32 v163, v175, v163
	v_max3_f32 v162, v162, v164, v165
	v_mov_b32_e32 v167, v163
	v_max3_f32 v170, v162, v166, v167
	v_sub_f32_e32 v162, v131, v192
	v_add_f32_e32 v162, v176, v162
	v_sub_f32_e32 v163, v131, v193
	v_add_f32_e32 v163, v177, v163
	v_sub_f32_e32 v171, v131, v178
	v_add_f32_e32 v100, v100, v171
	v_sub_f32_e32 v171, v131, v179
	v_add_f32_e32 v101, v101, v171
	v_sub_f32_e32 v171, v131, v180
	v_add_f32_e32 v102, v102, v171
	v_sub_f32_e32 v171, v131, v181
	v_add_f32_e32 v103, v103, v171
	v_sub_f32_e32 v171, v131, v182
	v_add_f32_e32 v96, v96, v171
	v_sub_f32_e32 v171, v131, v183
	v_add_f32_e32 v97, v97, v171
	v_sub_f32_e32 v171, v131, v184
	v_max3_f32 v170, v170, v162, v163
	v_add_f32_e32 v98, v98, v171
	v_max3_f32 v170, v170, v100, v101
	v_sub_f32_e32 v168, v131, v185
	v_max3_f32 v170, v170, v102, v103
	v_add_f32_e32 v99, v99, v168
	v_max3_f32 v170, v170, v96, v97
	s_branch .Lfox_join
